# attention prologue critical-first load ordering: first-supertile K/V loads issued before the q-norm gain loads
# speedup vs baseline: 1.0002x; 1.0002x over previous
.LBB0_146:
	s_or_b64 exec, exec, s[44:45]
	s_ashr_i32 s3, s4, 1
	s_andn2_b32 s3, s3, 31
	v_and_b32_e32 v47, 31, v40
	s_add_i32 s3, s3, s11
	v_or_b32_e32 v202, s3, v47
	v_ashrrev_i32_e32 v203, 31, v202
	v_lshl_add_u64 v[0:1], v[202:203], 2, s[20:21]
	global_load_dword v237, v[0:1], off sc1
	v_lshl_add_u64 v[0:1], s[36:37], 0, v[202:203]
	v_readlane_b32 s14, v253, 43
	v_lshlrev_b64 v[0:1], 11, v[0:1]
	v_readlane_b32 s15, v253, 44
	v_bfe_u32 v45, v40, 5, 1
	s_lshl_b32 s36, s5, 1
	v_lshl_add_u64 v[0:1], s[14:15], 0, v[0:1]
	v_lshl_add_u64 v[200:201], v[0:1], 0, s[36:37]
	v_lshlrev_b32_e32 v49, 4, v45
	v_lshrrev_b32_e32 v98, 3, v47
	v_lshl_add_u32 v98, v45, 2, v98
	v_sub_u32_e32 v99, v98, v47
	v_lshl_add_u32 v99, v99, 11, v200
	v_and_b32_e32 v100, 7, v47
	v_lshl_add_u32 v99, v100, 4, v99
	v_subrev_u32_e32 v99, s74, v99
	v_mul_u32_u24_e32 v101, 0x90, v98
	v_lshl_add_u32 v101, v100, 4, v101
	v_and_b32_e32 v100, 0x1c0, v40
	v_mul_u32_u24_e32 v100, 0x48, v100
	v_add_u32_e32 v100, 0x11800, v100
	v_add_u32_e32 v101, v101, v100
	v_mul_u32_u24_e32 v98, 0x90, v47
	v_add3_u32 v100, v100, v98, v49
	buffer_load_dwordx4 v[0:3], v99, s[76:79], 0 offen sc1
	v_add_u32_e32 v98, 0x4000, v99
	buffer_load_dwordx4 v[36:39], v98, s[76:79], 0 offen sc1
	v_add_u32_e32 v98, 0x8000, v99
	buffer_load_dwordx4 v[74:77], v98, s[76:79], 0 offen sc1
	v_add_u32_e32 v98, 0xc000, v99
	buffer_load_dwordx4 v[62:65], v98, s[76:79], 0 offen sc1
	buffer_load_dwordx4 v[106:109], v106, s[76:79], 0 offen sc1
	buffer_load_dwordx4 v[110:113], v110, s[76:79], 0 offen sc1
	buffer_load_dwordx4 v[114:117], v114, s[76:79], 0 offen sc1
	buffer_load_dwordx4 v[118:121], v118, s[76:79], 0 offen sc1
	buffer_load_dwordx4 v[122:125], v122, s[76:79], 0 offen sc1
	buffer_load_dwordx4 v[126:129], v126, s[76:79], 0 offen sc1
	buffer_load_dwordx4 v[130:133], v130, s[76:79], 0 offen sc1
	buffer_load_dwordx4 v[134:137], v134, s[76:79], 0 offen sc1
	v_and_b32_e32 v5, 64, v227
	v_xor_b32_e32 v4, 32, v227
	v_add_u32_e32 v51, 64, v5
	s_lshl_b32 s5, s5, 2
	v_cmp_lt_i32_e32 vcc, v4, v51
	s_add_u32 s14, s70, s5
	s_addc_u32 s15, s71, 0
	v_cndmask_b32_e32 v4, v227, v4, vcc
	v_lshlrev_b32_e32 v8, 5, v45
	v_lshlrev_b32_e32 v140, 2, v4
	global_load_dwordx4 v[28:31], v8, s[14:15] offset:16
	global_load_dwordx4 v[32:35], v8, s[14:15]
	global_load_dwordx4 v[20:23], v8, s[14:15] offset:80
	global_load_dwordx4 v[24:27], v8, s[14:15] offset:64
	global_load_dwordx4 v[12:15], v8, s[14:15] offset:144
	global_load_dwordx4 v[16:19], v8, s[14:15] offset:128
	global_load_dwordx4 v[4:7], v8, s[14:15] offset:208
	s_nop 0
	global_load_dwordx4 v[8:11], v8, s[14:15] offset:192
	s_movk_i32 s11, 0x210
	v_mul_lo_u32 v218, v44, s11
	v_mul_lo_u32 v219, v46, s11
	v_mul_lo_u32 v220, v48, s11
	v_mul_lo_u32 v221, v50, s11
	v_readlane_b32 s11, v254, 25
	v_lshl_add_u64 v[206:207], v[40:41], 2, s[20:21]
	v_lshlrev_b32_e32 v193, 2, v45
	v_add_u32_e32 v231, 0, v49
	v_mov_b32_e32 v41, v97
	v_mov_b32_e32 v44, v97
	v_mov_b32_e32 v46, v97
	s_mov_b32 s4, 0
	s_or_b32 s5, s3, 31
	v_mov_b32_e32 v234, 0
	s_waitcnt vmcnt(16)
	ds_write_b128 v101, v[0:3]
	ds_write_b128 v101, v[36:39] offset:1152
	ds_write_b128 v101, v[74:77] offset:2304
	ds_write_b128 v101, v[62:65] offset:3456
	ds_read_b128 v[0:3], v100
	ds_read_b128 v[36:39], v100 offset:32
	ds_read_b128 v[74:77], v100 offset:64
	ds_read_b128 v[62:65], v100 offset:96
	s_waitcnt lgkmcnt(0)
	v_lshlrev_b32_e32 v86, 16, v3
	v_and_b32_e32 v87, 0xffff0000, v3
	v_lshlrev_b32_e32 v92, 16, v1
	s_waitcnt vmcnt(16)
	v_and_b32_e32 v53, 0xffff0000, v65
	v_and_b32_e32 v55, 0xffff0000, v64
	v_lshlrev_b32_e32 v52, 16, v65
	v_lshlrev_b32_e32 v54, 16, v64
	v_mov_b32_e32 v58, v53
	v_mov_b32_e32 v59, v55
	v_mov_b32_e32 v56, v52
	v_mov_b32_e32 v57, v54
	v_pk_mul_f32 v[58:59], v[58:59], v[58:59]
	v_and_b32_e32 v93, 0xffff0000, v1
	v_pk_fma_f32 v[60:61], v[56:57], v[56:57], v[58:59]
	v_and_b32_e32 v57, 0xffff0000, v63
	v_and_b32_e32 v59, 0xffff0000, v62
	v_lshlrev_b32_e32 v56, 16, v63
	v_lshlrev_b32_e32 v58, 16, v62
	v_mov_b32_e32 v64, v57
	v_mov_b32_e32 v65, v59
	v_mov_b32_e32 v62, v56
	v_mov_b32_e32 v63, v58
	v_pk_mul_f32 v[64:65], v[64:65], v[64:65]
	v_lshlrev_b32_e32 v138, 16, v0
	v_pk_fma_f32 v[66:67], v[62:63], v[62:63], v[64:65]
	v_and_b32_e32 v63, 0xffff0000, v77
	v_and_b32_e32 v65, 0xffff0000, v76
	v_lshlrev_b32_e32 v62, 16, v77
	v_lshlrev_b32_e32 v64, 16, v76
	v_mov_b32_e32 v70, v63
	v_mov_b32_e32 v71, v65
	v_mov_b32_e32 v68, v62
	v_mov_b32_e32 v69, v64
	v_pk_mul_f32 v[70:71], v[70:71], v[70:71]
	v_and_b32_e32 v139, 0xffff0000, v0
	v_pk_fma_f32 v[72:73], v[68:69], v[68:69], v[70:71]
	v_and_b32_e32 v69, 0xffff0000, v75
	v_and_b32_e32 v71, 0xffff0000, v74
	v_lshlrev_b32_e32 v68, 16, v75
	v_lshlrev_b32_e32 v70, 16, v74
	v_mov_b32_e32 v76, v69
	v_mov_b32_e32 v77, v71
	v_mov_b32_e32 v74, v68
	v_mov_b32_e32 v75, v70
	v_pk_mul_f32 v[76:77], v[76:77], v[76:77]
	v_and_b32_e32 v79, 0xffff0000, v38
	v_pk_fma_f32 v[76:77], v[74:75], v[74:75], v[76:77]
	v_and_b32_e32 v75, 0xffff0000, v39
	v_pk_mul_f32 v[88:89], v[86:87], v[86:87]
	v_lshlrev_b32_e32 v90, 16, v2
	v_and_b32_e32 v91, 0xffff0000, v2
	v_pk_mul_f32 v[94:95], v[92:93], v[92:93]
	v_pk_mul_f32 v[0:1], v[138:139], v[138:139]
	v_lshlrev_b32_e32 v74, 16, v39
	v_lshlrev_b32_e32 v78, 16, v38
	v_mov_b32_e32 v80, v75
	v_mov_b32_e32 v81, v79
	v_pk_mul_f32 v[2:3], v[90:91], v[90:91]
	v_add_f32_e32 v88, v88, v89
	v_add_f32_e32 v89, v94, v95
	v_add_f32_e32 v0, v0, v1
	v_mov_b32_e32 v38, v74
	v_mov_b32_e32 v39, v78
	v_pk_mul_f32 v[80:81], v[80:81], v[80:81]
	v_lshlrev_b32_e32 v84, 16, v36
	v_and_b32_e32 v85, 0xffff0000, v36
	v_add_f32_e32 v0, v0, v89
	v_add_f32_e32 v1, v2, v3
	v_pk_fma_f32 v[38:39], v[38:39], v[38:39], v[80:81]
	v_lshlrev_b32_e32 v80, 16, v37
	v_and_b32_e32 v81, 0xffff0000, v37
	v_pk_mul_f32 v[36:37], v[84:85], v[84:85]
	v_add_f32_e32 v0, v1, v0
	v_pk_mul_f32 v[82:83], v[80:81], v[80:81]
	v_add_f32_e32 v0, v88, v0
	v_add_f32_e32 v1, v36, v37
	v_add_f32_e32 v0, v1, v0
	v_add_f32_e32 v1, v82, v83
	v_add_f32_e32 v0, v1, v0
	v_add_f32_e32 v0, v39, v0
	v_add_f32_e32 v0, v38, v0
	v_add_f32_e32 v0, v77, v0
	v_add_f32_e32 v0, v76, v0
	v_add_f32_e32 v0, v73, v0
	v_add_f32_e32 v0, v72, v0
	v_add_f32_e32 v0, v67, v0
	v_add_f32_e32 v0, v66, v0
	v_add_f32_e32 v0, v61, v0
	v_add_f32_e32 v0, v60, v0
	ds_bpermute_b32 v1, v140, v0
	v_mov_b32_e32 v36, v97
	v_mov_b32_e32 v37, v97
	v_mov_b32_e32 v38, v97
	v_mov_b32_e32 v39, v97
	s_waitcnt lgkmcnt(0)
	v_add_f32_e32 v0, v0, v1
	v_fmamk_f32 v0, v0, 0x3c800000, v225
	v_cmp_gt_f32_e32 vcc, s30, v0
	v_mul_f32_e32 v1, 0x4b800000, v0
	s_nop 0
	v_cndmask_b32_e32 v0, v0, v1, vcc
	v_rsq_f32_e32 v0, v0
	s_nop 0
	v_mul_f32_e32 v1, 0x45800000, v0
	v_cndmask_b32_e32 v0, v0, v1, vcc
	v_mul_f32_e32 v0, 0x3e38aa3b, v0
	v_pk_mul_f32 v[2:3], v[0:1], v[138:139] op_sel_hi:[0,1]
	s_waitcnt vmcnt(6)
	v_pk_mul_f32 v[2:3], v[32:33], v[2:3]
	v_mov_b32_e32 v32, v97
	v_cvt_pk_bf16_f32 v138, v2, v3
	v_pk_mul_f32 v[2:3], v[0:1], v[92:93] op_sel_hi:[0,1]
	v_pk_mul_f32 v[2:3], v[34:35], v[2:3]
	v_mov_b32_e32 v33, v97
	v_cvt_pk_bf16_f32 v139, v2, v3
	v_pk_mul_f32 v[2:3], v[0:1], v[90:91] op_sel_hi:[0,1]
	v_pk_mul_f32 v[2:3], v[28:29], v[2:3]
	v_mov_b32_e32 v34, v97
	v_cvt_pk_bf16_f32 v140, v2, v3
	v_pk_mul_f32 v[2:3], v[0:1], v[86:87] op_sel_hi:[0,1]
	v_pk_mul_f32 v[2:3], v[30:31], v[2:3]
	v_mov_b32_e32 v35, v97
	v_cvt_pk_bf16_f32 v141, v2, v3
	v_pk_mul_f32 v[2:3], v[0:1], v[84:85] op_sel_hi:[0,1]
	s_waitcnt vmcnt(4)
	v_pk_mul_f32 v[2:3], v[24:25], v[2:3]
	s_nop 0
	v_cvt_pk_bf16_f32 v142, v2, v3
	v_pk_mul_f32 v[2:3], v[0:1], v[80:81] op_sel_hi:[0,1]
	v_pk_mul_f32 v[2:3], v[26:27], v[2:3]
	s_nop 0
	v_cvt_pk_bf16_f32 v143, v2, v3
	v_pk_mul_f32 v[2:3], v[0:1], v[78:79] op_sel_hi:[0,1]
	v_pk_mul_f32 v[2:3], v[20:21], v[2:3]
	s_nop 0
	v_cvt_pk_bf16_f32 v144, v2, v3
	v_pk_mul_f32 v[2:3], v[0:1], v[74:75] op_sel_hi:[0,1]
	v_pk_mul_f32 v[2:3], v[22:23], v[2:3]
	s_nop 0
	v_cvt_pk_bf16_f32 v145, v2, v3
	v_pk_mul_f32 v[2:3], v[0:1], v[70:71] op_sel_hi:[0,1]
	s_waitcnt vmcnt(2)
	v_pk_mul_f32 v[2:3], v[16:17], v[2:3]
	v_xor_b32_e32 v16, 1, v227
	v_cvt_pk_bf16_f32 v146, v2, v3
	v_pk_mul_f32 v[2:3], v[0:1], v[68:69] op_sel_hi:[0,1]
	v_pk_mul_f32 v[2:3], v[18:19], v[2:3]
	v_cmp_lt_i32_e32 vcc, v16, v51
	v_cvt_pk_bf16_f32 v147, v2, v3
	v_pk_mul_f32 v[2:3], v[0:1], v[64:65] op_sel_hi:[0,1]
	v_pk_mul_f32 v[2:3], v[12:13], v[2:3]
	v_cndmask_b32_e32 v16, v227, v16, vcc
	v_cvt_pk_bf16_f32 v148, v2, v3
	v_pk_mul_f32 v[2:3], v[0:1], v[62:63] op_sel_hi:[0,1]
	v_pk_mul_f32 v[2:3], v[14:15], v[2:3]
	v_lshlrev_b32_e32 v191, 2, v16
	v_cvt_pk_bf16_f32 v149, v2, v3
	v_pk_mul_f32 v[2:3], v[0:1], v[58:59] op_sel_hi:[0,1]
	s_waitcnt vmcnt(0)
	v_pk_mul_f32 v[2:3], v[8:9], v[2:3]
	v_xor_b32_e32 v16, 2, v227
	v_cvt_pk_bf16_f32 v150, v2, v3
	v_pk_mul_f32 v[2:3], v[0:1], v[56:57] op_sel_hi:[0,1]
	v_pk_mul_f32 v[2:3], v[10:11], v[2:3]
	v_cmp_lt_i32_e32 vcc, v16, v51
	v_cvt_pk_bf16_f32 v151, v2, v3
	v_pk_mul_f32 v[2:3], v[0:1], v[54:55] op_sel_hi:[0,1]
	v_pk_mul_f32 v[0:1], v[0:1], v[52:53] op_sel_hi:[0,1]
	v_pk_mul_f32 v[0:1], v[6:7], v[0:1]
	v_cndmask_b32_e32 v16, v227, v16, vcc
	v_cvt_pk_bf16_f32 v153, v0, v1
	s_nop 0
	v_mov_b32_e32 v0, v237
	v_lshlrev_b32_e32 v195, 2, v16
	v_xor_b32_e32 v16, 4, v227
	v_cmp_lt_i32_e32 vcc, v16, v51
	v_mov_b32_e32 v17, v97
	v_pk_mul_f32 v[2:3], v[4:5], v[2:3]
	v_cndmask_b32_e32 v16, v227, v16, vcc
	v_lshlrev_b32_e32 v197, 2, v16
	v_lshlrev_b32_e32 v16, 4, v40
	v_and_b32_e32 v199, 0x1f0, v16
	v_lshlrev_b32_e32 v16, 1, v43
	v_lshl_add_u64 v[204:205], s[12:13], 0, v[16:17]
	v_mul_u32_u24_e32 v17, 0x210, v47
	v_lshl_or_b32 v17, v45, 3, v17
	v_mul_u32_u24_e32 v16, 0x90, v47
	v_add_u32_e32 v232, s11, v17
	v_readlane_b32 s11, v254, 26
	v_cvt_pk_bf16_f32 v152, v2, v3
	v_lshlrev_b32_e32 v203, 2, v40
	v_mul_lo_u32 v205, v42, s93
	v_add3_u32 v233, v16, v49, s11
	v_mov_b32_e32 v40, v97
	v_mov_b32_e32 v42, v97
	v_mov_b32_e32 v43, v97
	v_mov_b32_e32 v45, v97
	v_mov_b32_e32 v47, v97
	v_mov_b64_e32 v[16:17], v[32:33]
	s_mov_b64 s[20:21], -1
	v_mov_b64_e32 v[18:19], v[34:35]
	v_mov_b64_e32 v[20:21], v[36:37]
	v_mov_b64_e32 v[22:23], v[38:39]
	v_mov_b64_e32 v[24:25], v[40:41]
	v_mov_b64_e32 v[26:27], v[42:43]
	v_mov_b64_e32 v[28:29], v[44:45]
	v_mov_b64_e32 v[30:31], v[46:47]
	s_waitcnt vmcnt(0)
	v_mov_b32_e32 v14, v0
	v_mov_b32_e32 v15, v0
	v_mov_b32_e32 v1, v0
	v_mov_b32_e32 v2, v0
	v_mov_b32_e32 v3, v0
	v_mov_b32_e32 v4, v0
	v_mov_b32_e32 v5, v0
	v_mov_b32_e32 v6, v0
	v_mov_b32_e32 v7, v0
	v_mov_b32_e32 v8, v0
	v_mov_b32_e32 v9, v0
	v_mov_b32_e32 v10, v0
	v_mov_b32_e32 v11, v0
	v_mov_b32_e32 v12, v0
	v_mov_b32_e32 v13, v0
	v_mov_b64_e32 v[62:63], v[14:15]
	v_mov_b64_e32 v[60:61], v[12:13]
	v_mov_b64_e32 v[58:59], v[10:11]
	v_mov_b64_e32 v[56:57], v[8:9]
	v_mov_b64_e32 v[54:55], v[6:7]
	v_mov_b64_e32 v[52:53], v[4:5]
	v_mov_b64_e32 v[50:51], v[2:3]
	v_mov_b64_e32 v[48:49], v[0:1]
	s_branch .LBB0_148
